# grid barrier: waiting workgroups poll the global generation word directly instead of their XCD leader's forwarded word (one hop fewer per barrier)
# baseline (speedup 1.0000x reference)
; __device__ __forceinline__ unsigned xb_ld(unsigned* p)              { return __hip_atomic_load(p, __ATOMIC_RELAXED, __HIP_MEMORY_SCOPE_AGENT); }
; __device__ __forceinline__ unsigned xb_add(unsigned* p, unsigned v) { return __hip_atomic_fetch_add(p, v, __ATOMIC_RELAXED, __HIP_MEMORY_SCOPE_AGENT); }
; #define XB_SPIN(cond, bar) do { unsigned _sp = 0; while (cond) { __builtin_amdgcn_s_sleep(1); \
;     if ((++_sp & 255u) == 0u) { if (xb_ld(&(bar)[XB_TMO])) break; if (_sp > XB_SPIN_CAP) { atomicAdd(&(bar)[XB_TMO], 1u); break; } } } } while (0)
; __device__ __forceinline__ void xcd_barrier(const XcdBarrier& b) {
;     ...
;         const unsigned old = xb_add(&bar[XB_XSUB(bx)], 1u);
;         const unsigned gen = old / nloc;
;         if (old + 1u == (gen + 1u) * nloc) {
;             __builtin_amdgcn_fence(__ATOMIC_RELEASE, "agent");
;             asm volatile("s_waitcnt vmcnt(0)" ::: "memory");
;             const unsigned og = xb_add(&bar[XB_TOP], 1u);
;             const unsigned tg = og / nx;
;             if (og + 1u == (tg + 1u) * nx) xb_add(&bar[XB_TOPGEN], 1u);
;             else XB_SPIN(xb_ld(&bar[XB_TOPGEN]) == tg, bar);
;             xb_add(&bar[XB_XGEN(bx)], 1u);
;             __builtin_amdgcn_fence(__ATOMIC_ACQUIRE, "agent");
;             asm volatile("s_waitcnt vmcnt(0)" ::: "memory");
;         } else {
;             XB_SPIN(xb_ld(&bar[XB_XGEN(bx)]) == gen, bar);
;             __builtin_amdgcn_fence(__ATOMIC_ACQUIRE, "agent");
;             asm volatile("s_waitcnt vmcnt(0)" ::: "memory");
.LBB0_245:
	s_or_b64 exec, exec, s[6:7]
	v_cvt_f32_u32_e32 v5, v3
	s_waitcnt vmcnt(0)
	v_readfirstlane_b32 s4, v4
	v_sub_u32_e32 v4, 0, v3
	v_rcp_iflag_f32_e32 v5, v5
	v_add_u32_e32 v6, s4, v2
	v_mul_f32_e32 v5, 0x4f7ffffe, v5
	v_cvt_u32_f32_e32 v5, v5
	v_mul_lo_u32 v2, v4, v5
	v_mul_hi_u32 v2, v5, v2
	v_add_u32_e32 v2, v5, v2
	v_mul_hi_u32 v2, v6, v2
	v_mul_lo_u32 v4, v2, v3
	v_sub_u32_e32 v4, v6, v4
	v_add_u32_e32 v5, 1, v2
	v_cmp_ge_u32_e32 vcc, v4, v3
	s_nop 1
	v_cndmask_b32_e32 v2, v2, v5, vcc
	v_sub_u32_e32 v5, v4, v3
	v_cndmask_b32_e32 v4, v4, v5, vcc
	v_add_u32_e32 v5, 1, v2
	v_cmp_ge_u32_e32 vcc, v4, v3
	v_add_u32_e32 v4, 1, v6
	s_nop 0
	v_cndmask_b32_e32 v2, v2, v5, vcc
	v_mul_lo_u32 v5, v3, v2
	v_add_u32_e32 v3, v5, v3
	v_cmp_ne_u32_e32 vcc, v4, v3
	s_and_saveexec_b64 s[4:5], vcc
	s_xor_b64 s[4:5], exec, s[4:5]
	s_cbranch_execz .LBB0_259
	s_waitcnt lgkmcnt(0)
	v_readlane_b32 s10, v249, 0
	v_readlane_b32 s11, v249, 1
	s_nop 3
	s_add_u32 s10, s10, 0x7500
	s_addc_u32 s11, s11, 0
	v_mov_b32_e32 v1, 0
	global_load_dword v1, v1, s[10:11] sc1
	s_waitcnt vmcnt(0)
	v_cmp_eq_u32_e32 vcc, v1, v2
	s_and_saveexec_b64 s[6:7], vcc
	s_cbranch_execz .LBB0_258
	v_readlane_b32 s12, v249, 0
	v_readlane_b32 s13, v249, 1
	s_add_u32 s8, s12, 0x4200
	v_readlane_b32 s14, v249, 2
	v_readlane_b32 s15, v249, 3
	s_addc_u32 s9, s13, 0
	s_mov_b32 s22, 1
	s_mov_b64 s[12:13], 0
	v_mov_b32_e32 v1, 0
	s_branch .LBB0_249

; __device__ __forceinline__ unsigned xb_ld(unsigned* p)              { return __hip_atomic_load(p, __ATOMIC_RELAXED, __HIP_MEMORY_SCOPE_AGENT); }
; __device__ __forceinline__ unsigned xb_add(unsigned* p, unsigned v) { return __hip_atomic_fetch_add(p, v, __ATOMIC_RELAXED, __HIP_MEMORY_SCOPE_AGENT); }
; #define XB_SPIN(cond, bar) do { unsigned _sp = 0; while (cond) { __builtin_amdgcn_s_sleep(1); \
;     if ((++_sp & 255u) == 0u) { if (xb_ld(&(bar)[XB_TMO])) break; if (_sp > XB_SPIN_CAP) { atomicAdd(&(bar)[XB_TMO], 1u); break; } } } } while (0)
; __device__ __forceinline__ void xcd_barrier(const XcdBarrier& b) {
;     ...
;         const unsigned old = xb_add(&bar[XB_XSUB(bx)], 1u);
;         const unsigned gen = old / nloc;
;         if (old + 1u == (gen + 1u) * nloc) {
;             __builtin_amdgcn_fence(__ATOMIC_RELEASE, "agent");
;             asm volatile("s_waitcnt vmcnt(0)" ::: "memory");
;             const unsigned og = xb_add(&bar[XB_TOP], 1u);
;             const unsigned tg = og / nx;
;             if (og + 1u == (tg + 1u) * nx) xb_add(&bar[XB_TOPGEN], 1u);
;             else XB_SPIN(xb_ld(&bar[XB_TOPGEN]) == tg, bar);
;             xb_add(&bar[XB_XGEN(bx)], 1u);
;             __builtin_amdgcn_fence(__ATOMIC_ACQUIRE, "agent");
;             asm volatile("s_waitcnt vmcnt(0)" ::: "memory");
;         } else {
;             XB_SPIN(xb_ld(&bar[XB_XGEN(bx)]) == gen, bar);
;             __builtin_amdgcn_fence(__ATOMIC_ACQUIRE, "agent");
;             asm volatile("s_waitcnt vmcnt(0)" ::: "memory");
.LBB0_504:
	s_or_b64 exec, exec, s[8:9]
	v_cvt_f32_u32_e32 v6, v4
	s_waitcnt vmcnt(0)
	v_readfirstlane_b32 s6, v5
	v_sub_u32_e32 v5, 0, v4
	v_rcp_iflag_f32_e32 v6, v6
	v_add_u32_e32 v7, s6, v3
	v_mul_f32_e32 v6, 0x4f7ffffe, v6
	v_cvt_u32_f32_e32 v6, v6
	v_mul_lo_u32 v3, v5, v6
	v_mul_hi_u32 v3, v6, v3
	v_add_u32_e32 v3, v6, v3
	v_mul_hi_u32 v3, v7, v3
	v_mul_lo_u32 v5, v3, v4
	v_sub_u32_e32 v5, v7, v5
	v_add_u32_e32 v6, 1, v3
	v_cmp_ge_u32_e32 vcc, v5, v4
	s_nop 1
	v_cndmask_b32_e32 v3, v3, v6, vcc
	v_sub_u32_e32 v6, v5, v4
	v_cndmask_b32_e32 v5, v5, v6, vcc
	v_add_u32_e32 v6, 1, v3
	v_cmp_ge_u32_e32 vcc, v5, v4
	v_add_u32_e32 v5, 1, v7
	s_nop 0
	v_cndmask_b32_e32 v3, v3, v6, vcc
	v_mul_lo_u32 v6, v4, v3
	v_add_u32_e32 v4, v6, v4
	v_cmp_ne_u32_e32 vcc, v5, v4
	s_and_saveexec_b64 s[6:7], vcc
	s_xor_b64 s[6:7], exec, s[6:7]
	s_cbranch_execz .LBB0_518
	s_waitcnt lgkmcnt(0)
	v_readlane_b32 s10, v251, 20
	v_readlane_b32 s11, v251, 21
	s_nop 4
	global_load_dword v2, v215, s[10:11] sc1
	s_waitcnt vmcnt(0)
	v_cmp_eq_u32_e32 vcc, v2, v3
	s_and_saveexec_b64 s[8:9], vcc
	s_cbranch_execz .LBB0_517
	s_mov_b32 s22, 1
	s_mov_b64 s[12:13], 0
	s_branch .LBB0_508

; __device__ __forceinline__ unsigned xb_ld(unsigned* p)              { return __hip_atomic_load(p, __ATOMIC_RELAXED, __HIP_MEMORY_SCOPE_AGENT); }
; __device__ __forceinline__ unsigned xb_add(unsigned* p, unsigned v) { return __hip_atomic_fetch_add(p, v, __ATOMIC_RELAXED, __HIP_MEMORY_SCOPE_AGENT); }
; #define XB_SPIN(cond, bar) do { unsigned _sp = 0; while (cond) { __builtin_amdgcn_s_sleep(1); \
;     if ((++_sp & 255u) == 0u) { if (xb_ld(&(bar)[XB_TMO])) break; if (_sp > XB_SPIN_CAP) { atomicAdd(&(bar)[XB_TMO], 1u); break; } } } } while (0)
; __device__ __forceinline__ void xcd_barrier(const XcdBarrier& b) {
;     ...
;         const unsigned old = xb_add(&bar[XB_XSUB(bx)], 1u);
;         const unsigned gen = old / nloc;
;         if (old + 1u == (gen + 1u) * nloc) {
;             __builtin_amdgcn_fence(__ATOMIC_RELEASE, "agent");
;             asm volatile("s_waitcnt vmcnt(0)" ::: "memory");
;             const unsigned og = xb_add(&bar[XB_TOP], 1u);
;             const unsigned tg = og / nx;
;             if (og + 1u == (tg + 1u) * nx) xb_add(&bar[XB_TOPGEN], 1u);
;             else XB_SPIN(xb_ld(&bar[XB_TOPGEN]) == tg, bar);
;             xb_add(&bar[XB_XGEN(bx)], 1u);
;             __builtin_amdgcn_fence(__ATOMIC_ACQUIRE, "agent");
;             asm volatile("s_waitcnt vmcnt(0)" ::: "memory");
;         } else {
;             XB_SPIN(xb_ld(&bar[XB_XGEN(bx)]) == gen, bar);
;             __builtin_amdgcn_fence(__ATOMIC_ACQUIRE, "agent");
;             asm volatile("s_waitcnt vmcnt(0)" ::: "memory");
.LBB0_682:
	s_or_b64 exec, exec, s[8:9]
	v_cvt_f32_u32_e32 v6, v4
	s_waitcnt vmcnt(0)
	v_readfirstlane_b32 s6, v5
	v_sub_u32_e32 v5, 0, v4
	v_rcp_iflag_f32_e32 v6, v6
	v_add_u32_e32 v7, s6, v3
	v_mul_f32_e32 v6, 0x4f7ffffe, v6
	v_cvt_u32_f32_e32 v6, v6
	v_mul_lo_u32 v3, v5, v6
	v_mul_hi_u32 v3, v6, v3
	v_add_u32_e32 v3, v6, v3
	v_mul_hi_u32 v3, v7, v3
	v_mul_lo_u32 v5, v3, v4
	v_sub_u32_e32 v5, v7, v5
	v_add_u32_e32 v6, 1, v3
	v_cmp_ge_u32_e32 vcc, v5, v4
	s_nop 1
	v_cndmask_b32_e32 v3, v3, v6, vcc
	v_sub_u32_e32 v6, v5, v4
	v_cndmask_b32_e32 v5, v5, v6, vcc
	v_add_u32_e32 v6, 1, v3
	v_cmp_ge_u32_e32 vcc, v5, v4
	v_add_u32_e32 v5, 1, v7
	s_nop 0
	v_cndmask_b32_e32 v3, v3, v6, vcc
	v_mul_lo_u32 v6, v4, v3
	v_add_u32_e32 v4, v6, v4
	v_cmp_ne_u32_e32 vcc, v5, v4
	s_and_saveexec_b64 s[6:7], vcc
	s_xor_b64 s[6:7], exec, s[6:7]
	s_cbranch_execz .LBB0_696
	s_waitcnt lgkmcnt(0)
	v_readlane_b32 s12, v251, 20
	v_readlane_b32 s13, v251, 21
	s_nop 4
	global_load_dword v2, v215, s[12:13] sc1
	s_waitcnt vmcnt(0)
	v_cmp_eq_u32_e32 vcc, v2, v3
	s_and_saveexec_b64 s[8:9], vcc
	s_cbranch_execz .LBB0_695
	s_mov_b32 s10, 1
	s_mov_b64 s[14:15], 0
	s_branch .LBB0_686

; __device__ __forceinline__ unsigned xb_ld(unsigned* p)              { return __hip_atomic_load(p, __ATOMIC_RELAXED, __HIP_MEMORY_SCOPE_AGENT); }
; __device__ __forceinline__ unsigned xb_add(unsigned* p, unsigned v) { return __hip_atomic_fetch_add(p, v, __ATOMIC_RELAXED, __HIP_MEMORY_SCOPE_AGENT); }
; #define XB_SPIN(cond, bar) do { unsigned _sp = 0; while (cond) { __builtin_amdgcn_s_sleep(1); \
;     if ((++_sp & 255u) == 0u) { if (xb_ld(&(bar)[XB_TMO])) break; if (_sp > XB_SPIN_CAP) { atomicAdd(&(bar)[XB_TMO], 1u); break; } } } } while (0)
; __device__ __forceinline__ void xcd_barrier(const XcdBarrier& b) {
;     ...
;         const unsigned old = xb_add(&bar[XB_XSUB(bx)], 1u);
;         const unsigned gen = old / nloc;
;         if (old + 1u == (gen + 1u) * nloc) {
;             __builtin_amdgcn_fence(__ATOMIC_RELEASE, "agent");
;             asm volatile("s_waitcnt vmcnt(0)" ::: "memory");
;             const unsigned og = xb_add(&bar[XB_TOP], 1u);
;             const unsigned tg = og / nx;
;             if (og + 1u == (tg + 1u) * nx) xb_add(&bar[XB_TOPGEN], 1u);
;             else XB_SPIN(xb_ld(&bar[XB_TOPGEN]) == tg, bar);
;             xb_add(&bar[XB_XGEN(bx)], 1u);
;             __builtin_amdgcn_fence(__ATOMIC_ACQUIRE, "agent");
;             asm volatile("s_waitcnt vmcnt(0)" ::: "memory");
;         } else {
;             XB_SPIN(xb_ld(&bar[XB_XGEN(bx)]) == gen, bar);
;             __builtin_amdgcn_fence(__ATOMIC_ACQUIRE, "agent");
;             asm volatile("s_waitcnt vmcnt(0)" ::: "memory");
.LBB0_1023:
	s_or_b64 exec, exec, s[12:13]
	v_cvt_f32_u32_e32 v6, v4
	s_waitcnt vmcnt(0)
	v_readfirstlane_b32 s6, v5
	v_sub_u32_e32 v5, 0, v4
	v_rcp_iflag_f32_e32 v6, v6
	v_add_u32_e32 v7, s6, v3
	v_mul_f32_e32 v6, 0x4f7ffffe, v6
	v_cvt_u32_f32_e32 v6, v6
	v_mul_lo_u32 v3, v5, v6
	v_mul_hi_u32 v3, v6, v3
	v_add_u32_e32 v3, v6, v3
	v_mul_hi_u32 v3, v7, v3
	v_mul_lo_u32 v5, v3, v4
	v_sub_u32_e32 v5, v7, v5
	v_add_u32_e32 v6, 1, v3
	v_cmp_ge_u32_e32 vcc, v5, v4
	s_nop 1
	v_cndmask_b32_e32 v3, v3, v6, vcc
	v_sub_u32_e32 v6, v5, v4
	v_cndmask_b32_e32 v5, v5, v6, vcc
	v_add_u32_e32 v6, 1, v3
	v_cmp_ge_u32_e32 vcc, v5, v4
	v_add_u32_e32 v5, 1, v7
	s_nop 0
	v_cndmask_b32_e32 v3, v3, v6, vcc
	v_mul_lo_u32 v6, v4, v3
	v_add_u32_e32 v4, v6, v4
	v_cmp_ne_u32_e32 vcc, v5, v4
	s_and_saveexec_b64 s[6:7], vcc
	s_xor_b64 s[6:7], exec, s[6:7]
	s_cbranch_execz .LBB0_1037
	s_waitcnt lgkmcnt(0)
	v_readlane_b32 s14, v251, 20
	v_readlane_b32 s15, v251, 21
	s_nop 4
	global_load_dword v2, v215, s[14:15] sc1
	s_waitcnt vmcnt(0)
	v_cmp_eq_u32_e32 vcc, v2, v3
	s_and_saveexec_b64 s[12:13], vcc
	s_cbranch_execz .LBB0_1036
	s_mov_b32 s8, 1
	s_mov_b64 s[16:17], 0
	s_branch .LBB0_1027

; __device__ __forceinline__ unsigned xb_ld(unsigned* p)              { return __hip_atomic_load(p, __ATOMIC_RELAXED, __HIP_MEMORY_SCOPE_AGENT); }
; __device__ __forceinline__ unsigned xb_add(unsigned* p, unsigned v) { return __hip_atomic_fetch_add(p, v, __ATOMIC_RELAXED, __HIP_MEMORY_SCOPE_AGENT); }
; #define XB_SPIN(cond, bar) do { unsigned _sp = 0; while (cond) { __builtin_amdgcn_s_sleep(1); \
;     if ((++_sp & 255u) == 0u) { if (xb_ld(&(bar)[XB_TMO])) break; if (_sp > XB_SPIN_CAP) { atomicAdd(&(bar)[XB_TMO], 1u); break; } } } } while (0)
; __device__ __forceinline__ void xcd_barrier(const XcdBarrier& b) {
;     ...
;         const unsigned old = xb_add(&bar[XB_XSUB(bx)], 1u);
;         const unsigned gen = old / nloc;
;         if (old + 1u == (gen + 1u) * nloc) {
;             __builtin_amdgcn_fence(__ATOMIC_RELEASE, "agent");
;             asm volatile("s_waitcnt vmcnt(0)" ::: "memory");
;             const unsigned og = xb_add(&bar[XB_TOP], 1u);
;             const unsigned tg = og / nx;
;             if (og + 1u == (tg + 1u) * nx) xb_add(&bar[XB_TOPGEN], 1u);
;             else XB_SPIN(xb_ld(&bar[XB_TOPGEN]) == tg, bar);
;             xb_add(&bar[XB_XGEN(bx)], 1u);
;             __builtin_amdgcn_fence(__ATOMIC_ACQUIRE, "agent");
;             asm volatile("s_waitcnt vmcnt(0)" ::: "memory");
;         } else {
;             XB_SPIN(xb_ld(&bar[XB_XGEN(bx)]) == gen, bar);
;             __builtin_amdgcn_fence(__ATOMIC_ACQUIRE, "agent");
;             asm volatile("s_waitcnt vmcnt(0)" ::: "memory");
.LBB0_1359:
	s_or_b64 exec, exec, s[16:17]
	v_cvt_f32_u32_e32 v6, v4
	s_waitcnt vmcnt(0)
	v_readfirstlane_b32 s6, v5
	v_sub_u32_e32 v5, 0, v4
	v_rcp_iflag_f32_e32 v6, v6
	v_add_u32_e32 v7, s6, v3
	v_mul_f32_e32 v6, 0x4f7ffffe, v6
	v_cvt_u32_f32_e32 v6, v6
	v_mul_lo_u32 v3, v5, v6
	v_mul_hi_u32 v3, v6, v3
	v_add_u32_e32 v3, v6, v3
	v_mul_hi_u32 v3, v7, v3
	v_mul_lo_u32 v5, v3, v4
	v_sub_u32_e32 v5, v7, v5
	v_add_u32_e32 v6, 1, v3
	v_cmp_ge_u32_e32 vcc, v5, v4
	s_nop 1
	v_cndmask_b32_e32 v3, v3, v6, vcc
	v_sub_u32_e32 v6, v5, v4
	v_cndmask_b32_e32 v5, v5, v6, vcc
	v_add_u32_e32 v6, 1, v3
	v_cmp_ge_u32_e32 vcc, v5, v4
	v_add_u32_e32 v5, 1, v7
	s_nop 0
	v_cndmask_b32_e32 v3, v3, v6, vcc
	v_mul_lo_u32 v6, v4, v3
	v_add_u32_e32 v4, v6, v4
	v_cmp_ne_u32_e32 vcc, v5, v4
	s_and_saveexec_b64 s[6:7], vcc
	s_xor_b64 s[6:7], exec, s[6:7]
	s_cbranch_execz .LBB0_1373
	s_waitcnt lgkmcnt(0)
	v_readlane_b32 s24, v251, 20
	v_readlane_b32 s25, v251, 21
	s_nop 4
	global_load_dword v2, v215, s[24:25] sc1
	s_waitcnt vmcnt(0)
	v_cmp_eq_u32_e32 vcc, v2, v3
	s_and_saveexec_b64 s[16:17], vcc
	s_cbranch_execz .LBB0_1372
	s_mov_b32 s8, 1
	s_mov_b64 s[26:27], 0
	s_branch .LBB0_1363

; __device__ __forceinline__ unsigned xb_ld(unsigned* p)              { return __hip_atomic_load(p, __ATOMIC_RELAXED, __HIP_MEMORY_SCOPE_AGENT); }
; __device__ __forceinline__ unsigned xb_add(unsigned* p, unsigned v) { return __hip_atomic_fetch_add(p, v, __ATOMIC_RELAXED, __HIP_MEMORY_SCOPE_AGENT); }
; #define XB_SPIN(cond, bar) do { unsigned _sp = 0; while (cond) { __builtin_amdgcn_s_sleep(1); \
;     if ((++_sp & 255u) == 0u) { if (xb_ld(&(bar)[XB_TMO])) break; if (_sp > XB_SPIN_CAP) { atomicAdd(&(bar)[XB_TMO], 1u); break; } } } } while (0)
; __device__ __forceinline__ void xcd_barrier(const XcdBarrier& b) {
;     ...
;         const unsigned old = xb_add(&bar[XB_XSUB(bx)], 1u);
;         const unsigned gen = old / nloc;
;         if (old + 1u == (gen + 1u) * nloc) {
;             __builtin_amdgcn_fence(__ATOMIC_RELEASE, "agent");
;             asm volatile("s_waitcnt vmcnt(0)" ::: "memory");
;             const unsigned og = xb_add(&bar[XB_TOP], 1u);
;             const unsigned tg = og / nx;
;             if (og + 1u == (tg + 1u) * nx) xb_add(&bar[XB_TOPGEN], 1u);
;             else XB_SPIN(xb_ld(&bar[XB_TOPGEN]) == tg, bar);
;             xb_add(&bar[XB_XGEN(bx)], 1u);
;             __builtin_amdgcn_fence(__ATOMIC_ACQUIRE, "agent");
;             asm volatile("s_waitcnt vmcnt(0)" ::: "memory");
;         } else {
;             XB_SPIN(xb_ld(&bar[XB_XGEN(bx)]) == gen, bar);
;             __builtin_amdgcn_fence(__ATOMIC_ACQUIRE, "agent");
;             asm volatile("s_waitcnt vmcnt(0)" ::: "memory");
.LBB0_1474:
	s_or_b64 exec, exec, s[16:17]
	v_cvt_f32_u32_e32 v6, v4
	s_waitcnt vmcnt(0)
	v_readfirstlane_b32 s6, v5
	v_sub_u32_e32 v5, 0, v4
	v_rcp_iflag_f32_e32 v6, v6
	v_add_u32_e32 v7, s6, v3
	v_mul_f32_e32 v6, 0x4f7ffffe, v6
	v_cvt_u32_f32_e32 v6, v6
	v_mul_lo_u32 v3, v5, v6
	v_mul_hi_u32 v3, v6, v3
	v_add_u32_e32 v3, v6, v3
	v_mul_hi_u32 v3, v7, v3
	v_mul_lo_u32 v5, v3, v4
	v_sub_u32_e32 v5, v7, v5
	v_add_u32_e32 v6, 1, v3
	v_cmp_ge_u32_e32 vcc, v5, v4
	s_nop 1
	v_cndmask_b32_e32 v3, v3, v6, vcc
	v_sub_u32_e32 v6, v5, v4
	v_cndmask_b32_e32 v5, v5, v6, vcc
	v_add_u32_e32 v6, 1, v3
	v_cmp_ge_u32_e32 vcc, v5, v4
	v_add_u32_e32 v5, 1, v7
	s_nop 0
	v_cndmask_b32_e32 v3, v3, v6, vcc
	v_mul_lo_u32 v6, v4, v3
	v_add_u32_e32 v4, v6, v4
	v_cmp_ne_u32_e32 vcc, v5, v4
	s_and_saveexec_b64 s[6:7], vcc
	s_xor_b64 s[6:7], exec, s[6:7]
	s_cbranch_execz .LBB0_1488
	s_waitcnt lgkmcnt(0)
	v_readlane_b32 s18, v251, 20
	v_readlane_b32 s19, v251, 21
	s_nop 4
	global_load_dword v2, v215, s[18:19] sc1
	s_waitcnt vmcnt(0)
	v_cmp_eq_u32_e32 vcc, v2, v3
	s_and_saveexec_b64 s[16:17], vcc
	s_cbranch_execz .LBB0_1487
	s_mov_b32 s8, 1
	s_mov_b64 s[22:23], 0
	s_branch .LBB0_1478

; __device__ __forceinline__ unsigned xb_ld(unsigned* p)              { return __hip_atomic_load(p, __ATOMIC_RELAXED, __HIP_MEMORY_SCOPE_AGENT); }
; __device__ __forceinline__ unsigned xb_add(unsigned* p, unsigned v) { return __hip_atomic_fetch_add(p, v, __ATOMIC_RELAXED, __HIP_MEMORY_SCOPE_AGENT); }
; #define XB_SPIN(cond, bar) do { unsigned _sp = 0; while (cond) { __builtin_amdgcn_s_sleep(1); \
;     if ((++_sp & 255u) == 0u) { if (xb_ld(&(bar)[XB_TMO])) break; if (_sp > XB_SPIN_CAP) { atomicAdd(&(bar)[XB_TMO], 1u); break; } } } } while (0)
; __device__ __forceinline__ void xcd_barrier(const XcdBarrier& b) {
;     ...
;         const unsigned old = xb_add(&bar[XB_XSUB(bx)], 1u);
;         const unsigned gen = old / nloc;
;         if (old + 1u == (gen + 1u) * nloc) {
;             __builtin_amdgcn_fence(__ATOMIC_RELEASE, "agent");
;             asm volatile("s_waitcnt vmcnt(0)" ::: "memory");
;             const unsigned og = xb_add(&bar[XB_TOP], 1u);
;             const unsigned tg = og / nx;
;             if (og + 1u == (tg + 1u) * nx) xb_add(&bar[XB_TOPGEN], 1u);
;             else XB_SPIN(xb_ld(&bar[XB_TOPGEN]) == tg, bar);
;             xb_add(&bar[XB_XGEN(bx)], 1u);
;             __builtin_amdgcn_fence(__ATOMIC_ACQUIRE, "agent");
;             asm volatile("s_waitcnt vmcnt(0)" ::: "memory");
;         } else {
;             XB_SPIN(xb_ld(&bar[XB_XGEN(bx)]) == gen, bar);
;             __builtin_amdgcn_fence(__ATOMIC_ACQUIRE, "agent");
;             asm volatile("s_waitcnt vmcnt(0)" ::: "memory");
.LBB0_1551:
	s_or_b64 exec, exec, s[10:11]
	v_cvt_f32_u32_e32 v6, v4
	s_waitcnt vmcnt(0)
	v_readfirstlane_b32 s6, v5
	v_sub_u32_e32 v5, 0, v4
	v_rcp_iflag_f32_e32 v6, v6
	v_add_u32_e32 v7, s6, v3
	v_mul_f32_e32 v6, 0x4f7ffffe, v6
	v_cvt_u32_f32_e32 v6, v6
	v_mul_lo_u32 v3, v5, v6
	v_mul_hi_u32 v3, v6, v3
	v_add_u32_e32 v3, v6, v3
	v_mul_hi_u32 v3, v7, v3
	v_mul_lo_u32 v5, v3, v4
	v_sub_u32_e32 v5, v7, v5
	v_add_u32_e32 v6, 1, v3
	v_cmp_ge_u32_e32 vcc, v5, v4
	s_nop 1
	v_cndmask_b32_e32 v3, v3, v6, vcc
	v_sub_u32_e32 v6, v5, v4
	v_cndmask_b32_e32 v5, v5, v6, vcc
	v_add_u32_e32 v6, 1, v3
	v_cmp_ge_u32_e32 vcc, v5, v4
	v_add_u32_e32 v5, 1, v7
	s_nop 0
	v_cndmask_b32_e32 v3, v3, v6, vcc
	v_mul_lo_u32 v6, v4, v3
	v_add_u32_e32 v4, v6, v4
	v_cmp_ne_u32_e32 vcc, v5, v4
	s_and_saveexec_b64 s[6:7], vcc
	s_xor_b64 s[6:7], exec, s[6:7]
	s_cbranch_execz .LBB0_1565
	s_waitcnt lgkmcnt(0)
	v_readlane_b32 s16, v251, 20
	v_readlane_b32 s17, v251, 21
	s_nop 4
	global_load_dword v2, v215, s[16:17] sc1
	s_waitcnt vmcnt(0)
	v_cmp_eq_u32_e32 vcc, v2, v3
	s_and_saveexec_b64 s[10:11], vcc
	s_cbranch_execz .LBB0_1564
	s_mov_b32 s8, 1
	s_mov_b64 s[18:19], 0
	s_branch .LBB0_1555

; __device__ __forceinline__ unsigned xb_ld(unsigned* p)              { return __hip_atomic_load(p, __ATOMIC_RELAXED, __HIP_MEMORY_SCOPE_AGENT); }
; __device__ __forceinline__ unsigned xb_add(unsigned* p, unsigned v) { return __hip_atomic_fetch_add(p, v, __ATOMIC_RELAXED, __HIP_MEMORY_SCOPE_AGENT); }
; #define XB_SPIN(cond, bar) do { unsigned _sp = 0; while (cond) { __builtin_amdgcn_s_sleep(1); \
;     if ((++_sp & 255u) == 0u) { if (xb_ld(&(bar)[XB_TMO])) break; if (_sp > XB_SPIN_CAP) { atomicAdd(&(bar)[XB_TMO], 1u); break; } } } } while (0)
; __device__ __forceinline__ void xcd_barrier(const XcdBarrier& b) {
;     ...
;         const unsigned old = xb_add(&bar[XB_XSUB(bx)], 1u);
;         const unsigned gen = old / nloc;
;         if (old + 1u == (gen + 1u) * nloc) {
;             __builtin_amdgcn_fence(__ATOMIC_RELEASE, "agent");
;             asm volatile("s_waitcnt vmcnt(0)" ::: "memory");
;             const unsigned og = xb_add(&bar[XB_TOP], 1u);
;             const unsigned tg = og / nx;
;             if (og + 1u == (tg + 1u) * nx) xb_add(&bar[XB_TOPGEN], 1u);
;             else XB_SPIN(xb_ld(&bar[XB_TOPGEN]) == tg, bar);
;             xb_add(&bar[XB_XGEN(bx)], 1u);
;             __builtin_amdgcn_fence(__ATOMIC_ACQUIRE, "agent");
;             asm volatile("s_waitcnt vmcnt(0)" ::: "memory");
;         } else {
;             XB_SPIN(xb_ld(&bar[XB_XGEN(bx)]) == gen, bar);
;             __builtin_amdgcn_fence(__ATOMIC_ACQUIRE, "agent");
;             asm volatile("s_waitcnt vmcnt(0)" ::: "memory");
.LBB0_1669:
	s_or_b64 exec, exec, s[10:11]
	v_cvt_f32_u32_e32 v6, v4
	s_waitcnt vmcnt(0)
	v_readfirstlane_b32 s6, v5
	v_sub_u32_e32 v5, 0, v4
	v_rcp_iflag_f32_e32 v6, v6
	v_add_u32_e32 v7, s6, v3
	v_mul_f32_e32 v6, 0x4f7ffffe, v6
	v_cvt_u32_f32_e32 v6, v6
	v_mul_lo_u32 v3, v5, v6
	v_mul_hi_u32 v3, v6, v3
	v_add_u32_e32 v3, v6, v3
	v_mul_hi_u32 v3, v7, v3
	v_mul_lo_u32 v5, v3, v4
	v_sub_u32_e32 v5, v7, v5
	v_add_u32_e32 v6, 1, v3
	v_cmp_ge_u32_e32 vcc, v5, v4
	s_nop 1
	v_cndmask_b32_e32 v3, v3, v6, vcc
	v_sub_u32_e32 v6, v5, v4
	v_cndmask_b32_e32 v5, v5, v6, vcc
	v_add_u32_e32 v6, 1, v3
	v_cmp_ge_u32_e32 vcc, v5, v4
	v_add_u32_e32 v5, 1, v7
	s_nop 0
	v_cndmask_b32_e32 v3, v3, v6, vcc
	v_mul_lo_u32 v6, v4, v3
	v_add_u32_e32 v4, v6, v4
	v_cmp_ne_u32_e32 vcc, v5, v4
	s_and_saveexec_b64 s[6:7], vcc
	s_xor_b64 s[6:7], exec, s[6:7]
	s_cbranch_execz .LBB0_1683
	s_waitcnt lgkmcnt(0)
	v_readlane_b32 s14, v251, 20
	v_readlane_b32 s15, v251, 21
	s_nop 4
	global_load_dword v2, v215, s[14:15] sc1
	s_waitcnt vmcnt(0)
	v_cmp_eq_u32_e32 vcc, v2, v3
	s_and_saveexec_b64 s[10:11], vcc
	s_cbranch_execz .LBB0_1682
	s_mov_b32 s8, 1
	s_mov_b64 s[16:17], 0
	s_branch .LBB0_1673

; __device__ __forceinline__ unsigned xb_ld(unsigned* p)              { return __hip_atomic_load(p, __ATOMIC_RELAXED, __HIP_MEMORY_SCOPE_AGENT); }
; __device__ __forceinline__ unsigned xb_add(unsigned* p, unsigned v) { return __hip_atomic_fetch_add(p, v, __ATOMIC_RELAXED, __HIP_MEMORY_SCOPE_AGENT); }
; #define XB_SPIN(cond, bar) do { unsigned _sp = 0; while (cond) { __builtin_amdgcn_s_sleep(1); \
;     if ((++_sp & 255u) == 0u) { if (xb_ld(&(bar)[XB_TMO])) break; if (_sp > XB_SPIN_CAP) { atomicAdd(&(bar)[XB_TMO], 1u); break; } } } } while (0)
; __device__ __forceinline__ void xcd_barrier(const XcdBarrier& b) {
;     ...
;         const unsigned old = xb_add(&bar[XB_XSUB(bx)], 1u);
;         const unsigned gen = old / nloc;
;         if (old + 1u == (gen + 1u) * nloc) {
;             __builtin_amdgcn_fence(__ATOMIC_RELEASE, "agent");
;             asm volatile("s_waitcnt vmcnt(0)" ::: "memory");
;             const unsigned og = xb_add(&bar[XB_TOP], 1u);
;             const unsigned tg = og / nx;
;             if (og + 1u == (tg + 1u) * nx) xb_add(&bar[XB_TOPGEN], 1u);
;             else XB_SPIN(xb_ld(&bar[XB_TOPGEN]) == tg, bar);
;             xb_add(&bar[XB_XGEN(bx)], 1u);
;             __builtin_amdgcn_fence(__ATOMIC_ACQUIRE, "agent");
;             asm volatile("s_waitcnt vmcnt(0)" ::: "memory");
;         } else {
;             XB_SPIN(xb_ld(&bar[XB_XGEN(bx)]) == gen, bar);
;             __builtin_amdgcn_fence(__ATOMIC_ACQUIRE, "agent");
;             asm volatile("s_waitcnt vmcnt(0)" ::: "memory");
.LBB0_1991:
	s_or_b64 exec, exec, s[6:7]
	v_cvt_f32_u32_e32 v6, v4
	s_waitcnt vmcnt(0)
	v_readfirstlane_b32 s4, v5
	v_sub_u32_e32 v5, 0, v4
	v_rcp_iflag_f32_e32 v6, v6
	v_add_u32_e32 v7, s4, v3
	v_mul_f32_e32 v6, 0x4f7ffffe, v6
	v_cvt_u32_f32_e32 v6, v6
	v_mul_lo_u32 v3, v5, v6
	v_mul_hi_u32 v3, v6, v3
	v_add_u32_e32 v3, v6, v3
	v_mul_hi_u32 v3, v7, v3
	v_mul_lo_u32 v5, v3, v4
	v_sub_u32_e32 v5, v7, v5
	v_add_u32_e32 v6, 1, v3
	v_cmp_ge_u32_e32 vcc, v5, v4
	s_nop 1
	v_cndmask_b32_e32 v3, v3, v6, vcc
	v_sub_u32_e32 v6, v5, v4
	v_cndmask_b32_e32 v5, v5, v6, vcc
	v_add_u32_e32 v6, 1, v3
	v_cmp_ge_u32_e32 vcc, v5, v4
	v_add_u32_e32 v5, 1, v7
	s_nop 0
	v_cndmask_b32_e32 v3, v3, v6, vcc
	v_mul_lo_u32 v6, v4, v3
	v_add_u32_e32 v4, v6, v4
	v_cmp_ne_u32_e32 vcc, v5, v4
	s_and_saveexec_b64 s[4:5], vcc
	s_xor_b64 s[4:5], exec, s[4:5]
	s_cbranch_execz .LBB0_2005
	s_waitcnt lgkmcnt(0)
	v_readlane_b32 s8, v251, 20
	v_readlane_b32 s9, v251, 21
	s_nop 4
	global_load_dword v2, v215, s[8:9] sc1
	s_waitcnt vmcnt(0)
	v_cmp_eq_u32_e32 vcc, v2, v3
	s_and_saveexec_b64 s[6:7], vcc
	s_cbranch_execz .LBB0_2004
	s_mov_b32 s20, 1
	s_mov_b64 s[10:11], 0
	s_branch .LBB0_1995
